# v30 + residual-epilogue row-statistics butterflies via v_permlane16/32_swap instead of ds_bpermute (no LDS round trips)
# baseline (speedup 1.0000x reference)
;     __device__ __forceinline__ void operator()(const f32x4 (&acc)[2][2][4][2], const Unit& u, int wr, int wc, int fr, int fq) const {
;     ...
;                 f16x8v ph[2][2];
; #pragma unroll
;                 for (int mm = 0; mm < 2; ++mm) { const size_t off = (size_t)(row0 + ai * HALF + (2 * mh + mm) * 16) * ldc + col0;
; #pragma unroll
;                     for (int bj = 0; bj < 2; ++bj) ph[mm][bj] = *(const f16x8v*)(xh + off + bj * HALF); }
; #pragma unroll
;                 for (int mm = 0; mm < 2; ++mm)
; #pragma unroll
;                     for (int bj = 0; bj < 2; ++bj) pre[mm][bj] = __builtin_convertvector(ph[mm][bj], f32x8v);
;             }
; #pragma unroll
;             for (int mm = 0; mm < 2; ++mm) {
;                 const int m = 2 * mh + mm;
;                 const int row = row0 + ai * HALF + m * 16; const size_t off = (size_t)row * ldc + col0;
;                 float q = 0.f;
; #pragma unroll
;                 for (int bj = 0; bj < 2; ++bj) {
;                     const f32x8v o = pre[mm][bj] + __builtin_shufflevector(acc[ai][bj][m][0], acc[ai][bj][m][1], 0, 1, 2, 3, 4, 5, 6, 7);
;                     if (!(pf & 2)) *(f16x8v*)(xh + off + bj * HALF) = __builtin_convertvector(o, f16x8v);
;                     q += ((o[0] * o[0] + o[1] * o[1]) + (o[2] * o[2] + o[3] * o[3])) + ((o[4] * o[4] + o[5] * o[5]) + (o[6] * o[6] + o[7] * o[7]));
;                 }
;                 if (!(pf & 4)) { q += __shfl_xor(q, 16); q += __shfl_xor(q, 32);
;                 if (fq == 0) ssn[(size_t)row * 32 + u.pn * 4 + wc] = q; }
.LBB0_348:
	v_lshl_or_b32 v148, s24, 8, v159
	v_lshl_add_u32 v150, s78, 8, v1
	v_ashrrev_i32_e32 v149, 31, v148
	v_lshlrev_b64 v[170:171], 1, v[148:149]
	v_ashrrev_i32_e32 v151, 31, v150
	v_lshl_add_u64 v[152:153], s[0:1], 0, v[170:171]
	v_lshlrev_b64 v[172:173], 12, v[150:151]
	v_lshl_add_u64 v[130:131], v[152:153], 0, v[172:173]
	global_load_dwordx4 v[162:165], v[130:131], off
	global_load_dwordx4 v[166:169], v[130:131], off offset:256
	v_or_b32_e32 v154, 16, v150
	v_ashrrev_i32_e32 v155, 31, v154
	v_lshlrev_b64 v[156:157], 12, v[154:155]
	v_lshl_add_u64 v[130:131], v[152:153], 0, v[156:157]
	global_load_dwordx4 v[134:137], v[130:131], off
	s_nop 0
	global_load_dwordx4 v[130:133], v[130:131], off offset:256
	v_and_b32_e32 v176, 64, v200
	v_xor_b32_e32 v161, 16, v200
	v_add_u32_e32 v176, 64, v176
	v_xor_b32_e32 v177, 32, v200
	v_cmp_lt_i32_e32 vcc, v161, v176
	v_lshl_add_u64 v[172:173], s[0:1], 0, v[172:173]
	v_lshl_add_u64 v[170:171], v[172:173], 0, v[170:171]
	v_cndmask_b32_e32 v161, v200, v161, vcc
	v_cmp_lt_i32_e32 vcc, v177, v176
	v_lshlrev_b32_e32 v161, 2, v161
	s_lshl_b32 s52, s24, 2
	v_cndmask_b32_e32 v188, v200, v177, vcc
	s_ashr_i32 s53, s52, 31
	s_waitcnt vmcnt(0)
	v_cvt_f32_f16_e32 v172, v165
	v_cvt_f32_f16_sdwa v173, v165 dst_sel:DWORD dst_unused:UNUSED_PAD src0_sel:WORD_1
	v_cvt_f32_f16_e32 v176, v164
	v_cvt_f32_f16_sdwa v177, v164 dst_sel:DWORD dst_unused:UNUSED_PAD src0_sel:WORD_1
	v_cvt_f32_f16_e32 v164, v163
	v_cvt_f32_f16_sdwa v165, v163 dst_sel:DWORD dst_unused:UNUSED_PAD src0_sel:WORD_1
	v_cvt_f32_f16_e32 v182, v162
	v_cvt_f32_f16_sdwa v183, v162 dst_sel:DWORD dst_unused:UNUSED_PAD src0_sel:WORD_1
	v_cvt_f32_f16_e32 v162, v169
	v_cvt_f32_f16_sdwa v163, v169 dst_sel:DWORD dst_unused:UNUSED_PAD src0_sel:WORD_1
	v_cvt_f32_f16_e32 v184, v168
	v_cvt_f32_f16_sdwa v185, v168 dst_sel:DWORD dst_unused:UNUSED_PAD src0_sel:WORD_1
	v_cvt_f32_f16_e32 v168, v167
	v_cvt_f32_f16_sdwa v169, v167 dst_sel:DWORD dst_unused:UNUSED_PAD src0_sel:WORD_1
	v_cvt_f32_f16_e32 v186, v166
	v_cvt_f32_f16_sdwa v187, v166 dst_sel:DWORD dst_unused:UNUSED_PAD src0_sel:WORD_1
	v_pk_add_f32 v[122:123], v[122:123], v[182:183]
	v_pk_add_f32 v[124:125], v[124:125], v[164:165]
	v_pk_add_f32 v[126:127], v[126:127], v[176:177]
	v_pk_add_f32 v[128:129], v[128:129], v[172:173]
	v_pk_add_f32 v[164:165], v[118:119], v[186:187]
	v_pk_add_f32 v[118:119], v[120:121], v[168:169]
	v_pk_add_f32 v[166:167], v[114:115], v[184:185]
	v_pk_add_f32 v[120:121], v[116:117], v[162:163]
	v_cvt_pk_f16_f32 v117, v128, v129
	v_cvt_pk_f16_f32 v116, v126, v127
	v_mul_f32_e32 v114, v123, v123
	v_mul_f32_e32 v115, v125, v125
	v_mul_f32_e32 v127, v127, v127
	v_mul_f32_e32 v129, v129, v129
	v_mul_f32_e32 v162, v165, v165
	v_mul_f32_e32 v163, v119, v119
	v_mul_f32_e32 v168, v167, v167
	v_mul_f32_e32 v169, v121, v121
	v_fmac_f32_e32 v114, v122, v122
	v_fmac_f32_e32 v115, v124, v124
	v_fmac_f32_e32 v127, v126, v126
	v_fmac_f32_e32 v129, v128, v128
	v_fmac_f32_e32 v162, v164, v164
	v_fmac_f32_e32 v163, v118, v118
	v_fmac_f32_e32 v168, v166, v166
	v_fmac_f32_e32 v169, v120, v120
	v_add_f32_e32 v114, v114, v115
	v_add_f32_e32 v115, v127, v129
	v_add_f32_e32 v126, v162, v163
	v_add_f32_e32 v127, v168, v169
	v_add_f32_e32 v114, v114, v115
	v_add_f32_e32 v115, v126, v127
	v_add_f32_e32 v126, v114, v115
	v_mov_b32_e32 v127, v126
	s_nop 1
	v_permlane16_swap_b32_e32 v127, v126
	v_cvt_pk_f16_f32 v115, v124, v125
	v_cvt_pk_f16_f32 v114, v122, v123
	global_store_dwordx4 v[170:171], v[114:117], off
	v_cvt_pk_f16_f32 v121, v120, v121
	v_cvt_pk_f16_f32 v120, v166, v167
	s_waitcnt lgkmcnt(0)
	v_add_f32_e32 v115, v126, v127
	v_lshlrev_b32_e32 v114, 2, v188
	v_mov_b32_e32 v116, v115
	s_nop 1
	v_permlane32_swap_b32_e32 v116, v115
	v_cvt_pk_f16_f32 v119, v118, v119
	v_cvt_pk_f16_f32 v118, v164, v165
	global_store_dwordx4 v[170:171], v[118:121], off offset:256
	s_and_saveexec_b64 s[54:55], s[36:37]
	s_cbranch_execz .LBB0_350
	v_lshlrev_b64 v[118:119], 7, v[150:151]
	v_lshl_add_u64 v[118:119], s[44:45], 0, v[118:119]
	v_lshl_add_u64 v[118:119], s[52:53], 2, v[118:119]
	s_lshl_b32 s24, s23, 2
	v_lshl_add_u64 v[118:119], v[118:119], 0, s[24:25]
	s_waitcnt lgkmcnt(0)
	v_add_f32_e32 v115, v115, v116
	global_store_dword v[118:119], v115, off
;     __device__ __forceinline__ void operator()(const f32x4 (&acc)[2][2][4][2], const Unit& u, int wr, int wc, int fr, int fq) const {
;     ...
;                 for (int mm = 0; mm < 2; ++mm) { const size_t off = (size_t)(row0 + ai * HALF + (2 * mh + mm) * 16) * ldc + col0;
; #pragma unroll
;                     for (int bj = 0; bj < 2; ++bj) ph[mm][bj] = *(const f16x8v*)(xh + off + bj * HALF); }
; #pragma unroll
;                 for (int mm = 0; mm < 2; ++mm)
; #pragma unroll
;                     for (int bj = 0; bj < 2; ++bj) pre[mm][bj] = __builtin_convertvector(ph[mm][bj], f32x8v);
;             }
; #pragma unroll
;             for (int mm = 0; mm < 2; ++mm) {
;                 const int m = 2 * mh + mm;
;                 const int row = row0 + ai * HALF + m * 16; const size_t off = (size_t)row * ldc + col0;
;                 float q = 0.f;
; #pragma unroll
;                 for (int bj = 0; bj < 2; ++bj) {
;                     const f32x8v o = pre[mm][bj] + __builtin_shufflevector(acc[ai][bj][m][0], acc[ai][bj][m][1], 0, 1, 2, 3, 4, 5, 6, 7);
;                     if (!(pf & 2)) *(f16x8v*)(xh + off + bj * HALF) = __builtin_convertvector(o, f16x8v);
;                     q += ((o[0] * o[0] + o[1] * o[1]) + (o[2] * o[2] + o[3] * o[3])) + ((o[4] * o[4] + o[5] * o[5]) + (o[6] * o[6] + o[7] * o[7]));
;                 }
;                 if (!(pf & 4)) { q += __shfl_xor(q, 16); q += __shfl_xor(q, 32);
;                 if (fq == 0) ssn[(size_t)row * 32 + u.pn * 4 + wc] = q; }
.LBB0_350:
	s_or_b64 exec, exec, s[54:55]
	v_cvt_f32_f16_sdwa v123, v134 dst_sel:DWORD dst_unused:UNUSED_PAD src0_sel:WORD_1
	v_cvt_f32_f16_e32 v122, v134
	v_cvt_f32_f16_sdwa v119, v136 dst_sel:DWORD dst_unused:UNUSED_PAD src0_sel:WORD_1
	v_cvt_f32_f16_sdwa v121, v135 dst_sel:DWORD dst_unused:UNUSED_PAD src0_sel:WORD_1
	v_cvt_f32_f16_e32 v118, v136
	v_cvt_f32_f16_e32 v120, v135
	v_cvt_f32_f16_sdwa v117, v137 dst_sel:DWORD dst_unused:UNUSED_PAD src0_sel:WORD_1
	s_waitcnt lgkmcnt(0)
	v_cvt_f32_f16_e32 v116, v137
	v_pk_add_f32 v[110:111], v[110:111], v[122:123]
	v_pk_add_f32 v[112:113], v[112:113], v[120:121]
	v_pk_add_f32 v[118:119], v[106:107], v[118:119]
	v_cvt_pk_f16_f32 v106, v110, v111
	v_mul_f32_e32 v111, v111, v111
	v_fmac_f32_e32 v111, v110, v110
	v_mul_f32_e32 v110, v113, v113
	v_cvt_f32_f16_sdwa v129, v131 dst_sel:DWORD dst_unused:UNUSED_PAD src0_sel:WORD_1
	v_cvt_f32_f16_sdwa v135, v130 dst_sel:DWORD dst_unused:UNUSED_PAD src0_sel:WORD_1
	v_cvt_f32_f16_e32 v128, v131
	v_cvt_f32_f16_e32 v134, v130
	v_pk_add_f32 v[116:117], v[108:109], v[116:117]
	v_fmac_f32_e32 v110, v112, v112
	v_cvt_f32_f16_sdwa v125, v133 dst_sel:DWORD dst_unused:UNUSED_PAD src0_sel:WORD_1
	v_cvt_f32_f16_sdwa v127, v132 dst_sel:DWORD dst_unused:UNUSED_PAD src0_sel:WORD_1
	v_cvt_f32_f16_e32 v124, v133
	v_cvt_f32_f16_e32 v126, v132
	v_cvt_pk_f16_f32 v107, v112, v113
	v_add_f32_e32 v110, v111, v110
	v_mul_f32_e32 v111, v119, v119
	v_mul_f32_e32 v112, v117, v117
	v_fmac_f32_e32 v111, v118, v118
	v_fmac_f32_e32 v112, v116, v116
	v_add_f32_e32 v111, v111, v112
	v_add_f32_e32 v115, v110, v111
	v_pk_add_f32 v[110:111], v[102:103], v[134:135]
	v_pk_add_f32 v[104:105], v[104:105], v[128:129]
	v_pk_add_f32 v[112:113], v[98:99], v[126:127]
	v_pk_add_f32 v[98:99], v[100:101], v[124:125]
	v_mul_f32_e32 v100, v111, v111
	v_mul_f32_e32 v101, v105, v105
	v_fmac_f32_e32 v100, v110, v110
	v_fmac_f32_e32 v101, v104, v104
	v_add_f32_e32 v100, v100, v101
	v_mul_f32_e32 v101, v113, v113
	v_mul_f32_e32 v102, v99, v99
	v_fmac_f32_e32 v101, v112, v112
	v_fmac_f32_e32 v102, v98, v98
	v_add_f32_e32 v101, v101, v102
	v_add_f32_e32 v100, v100, v101
	v_add_f32_e32 v102, v115, v100
	v_mov_b32_e32 v115, v102
	s_nop 1
	v_permlane16_swap_b32_e32 v115, v102
	v_cvt_pk_f16_f32 v103, v98, v99
	v_lshl_add_u64 v[100:101], s[0:1], 0, v[156:157]
	v_cvt_pk_f16_f32 v109, v116, v117
	v_cvt_pk_f16_f32 v108, v118, v119
	s_waitcnt lgkmcnt(0)
	v_add_f32_e32 v98, v102, v115
	v_mov_b32_e32 v99, v98
	s_nop 1
	v_permlane32_swap_b32_e32 v99, v98
	v_lshl_add_u64 v[116:117], v[148:149], 1, v[100:101]
	v_cvt_pk_f16_f32 v102, v112, v113
	v_cvt_pk_f16_f32 v101, v104, v105
	v_cvt_pk_f16_f32 v100, v110, v111
	global_store_dwordx4 v[116:117], v[106:109], off
	global_store_dwordx4 v[116:117], v[100:103], off offset:256
	s_and_saveexec_b64 s[54:55], s[36:37]
	s_cbranch_execz .LBB0_352
	v_lshlrev_b64 v[100:101], 7, v[154:155]
	v_lshl_add_u64 v[100:101], s[44:45], 0, v[100:101]
	v_lshl_add_u64 v[100:101], s[52:53], 2, v[100:101]
	s_lshl_b32 s24, s23, 2
	v_lshl_add_u64 v[100:101], v[100:101], 0, s[24:25]
	s_waitcnt lgkmcnt(0)
	v_add_f32_e32 v98, v98, v99
	global_store_dword v[100:101], v98, off
.LBB0_352:
	s_or_b64 exec, exec, s[54:55]
	v_or_b32_e32 v110, 32, v150
	v_ashrrev_i32_e32 v111, 31, v110
	v_lshlrev_b64 v[112:113], 12, v[110:111]
	s_waitcnt lgkmcnt(0)
	v_lshl_add_u64 v[98:99], v[152:153], 0, v[112:113]
	global_load_dwordx4 v[116:119], v[98:99], off
	global_load_dwordx4 v[120:123], v[98:99], off offset:256
	v_or_b32_e32 v106, 48, v150
	v_ashrrev_i32_e32 v107, 31, v106
	v_lshlrev_b64 v[108:109], 12, v[106:107]
	v_lshl_add_u64 v[98:99], v[152:153], 0, v[108:109]
	global_load_dwordx4 v[102:105], v[98:99], off
	s_nop 0
	global_load_dwordx4 v[98:101], v[98:99], off offset:256
	s_waitcnt vmcnt(3)
	v_cvt_f32_f16_e32 v124, v119
	v_cvt_f32_f16_sdwa v125, v119 dst_sel:DWORD dst_unused:UNUSED_PAD src0_sel:WORD_1
	v_cvt_f32_f16_e32 v126, v118
	v_cvt_f32_f16_sdwa v127, v118 dst_sel:DWORD dst_unused:UNUSED_PAD src0_sel:WORD_1
	v_cvt_f32_f16_e32 v118, v117
	v_cvt_f32_f16_sdwa v119, v117 dst_sel:DWORD dst_unused:UNUSED_PAD src0_sel:WORD_1
	v_cvt_f32_f16_e32 v128, v116
	v_cvt_f32_f16_sdwa v129, v116 dst_sel:DWORD dst_unused:UNUSED_PAD src0_sel:WORD_1
	s_waitcnt vmcnt(2)
	v_cvt_f32_f16_e32 v116, v123
	v_cvt_f32_f16_sdwa v117, v123 dst_sel:DWORD dst_unused:UNUSED_PAD src0_sel:WORD_1
	v_cvt_f32_f16_e32 v130, v122
	v_cvt_f32_f16_sdwa v131, v122 dst_sel:DWORD dst_unused:UNUSED_PAD src0_sel:WORD_1
	v_cvt_f32_f16_e32 v122, v121
	v_cvt_f32_f16_sdwa v123, v121 dst_sel:DWORD dst_unused:UNUSED_PAD src0_sel:WORD_1
	v_cvt_f32_f16_e32 v132, v120
	v_cvt_f32_f16_sdwa v133, v120 dst_sel:DWORD dst_unused:UNUSED_PAD src0_sel:WORD_1
	v_pk_add_f32 v[94:95], v[94:95], v[128:129]
	v_pk_add_f32 v[96:97], v[96:97], v[118:119]
	v_pk_add_f32 v[90:91], v[90:91], v[126:127]
	v_pk_add_f32 v[92:93], v[92:93], v[124:125]
	v_pk_add_f32 v[118:119], v[86:87], v[132:133]
	v_pk_add_f32 v[88:89], v[88:89], v[122:123]
	v_pk_add_f32 v[120:121], v[82:83], v[130:131]
	v_pk_add_f32 v[86:87], v[84:85], v[116:117]
	v_cvt_pk_f16_f32 v85, v92, v93
	v_cvt_pk_f16_f32 v84, v90, v91
	v_cvt_pk_f16_f32 v83, v96, v97
	v_cvt_pk_f16_f32 v82, v94, v95
	v_mul_f32_e32 v95, v95, v95
	v_mul_f32_e32 v97, v97, v97
	v_mul_f32_e32 v91, v91, v91
	v_mul_f32_e32 v93, v93, v93
	v_mul_f32_e32 v115, v119, v119
	v_mul_f32_e32 v116, v89, v89
	v_mul_f32_e32 v117, v121, v121
	v_mul_f32_e32 v122, v87, v87
	v_fmac_f32_e32 v95, v94, v94
	v_fmac_f32_e32 v97, v96, v96
	v_fmac_f32_e32 v91, v90, v90
	v_fmac_f32_e32 v93, v92, v92
	v_fmac_f32_e32 v115, v118, v118
	v_fmac_f32_e32 v116, v88, v88
	v_fmac_f32_e32 v117, v120, v120
	v_fmac_f32_e32 v122, v86, v86
	v_add_f32_e32 v90, v95, v97
	v_add_f32_e32 v91, v91, v93
	v_add_f32_e32 v92, v115, v116
	v_add_f32_e32 v93, v117, v122
	v_add_f32_e32 v90, v90, v91
	v_add_f32_e32 v91, v92, v93
	v_add_f32_e32 v92, v90, v91
	v_mov_b32_e32 v93, v92
	s_nop 1
	v_permlane16_swap_b32_e32 v93, v92
	v_lshl_add_u64 v[90:91], s[0:1], 0, v[112:113]
	v_lshl_add_u64 v[90:91], v[148:149], 1, v[90:91]
	global_store_dwordx4 v[90:91], v[82:85], off
	v_cvt_pk_f16_f32 v87, v86, v87
	v_cvt_pk_f16_f32 v86, v120, v121
	s_waitcnt lgkmcnt(0)
	v_add_f32_e32 v82, v92, v93
	v_mov_b32_e32 v83, v82
	s_nop 1
	v_permlane32_swap_b32_e32 v83, v82
	v_cvt_pk_f16_f32 v85, v88, v89
	v_cvt_pk_f16_f32 v84, v118, v119
	global_store_dwordx4 v[90:91], v[84:87], off offset:256
	s_and_saveexec_b64 s[54:55], s[36:37]
	s_cbranch_execz .LBB0_354
	v_lshlrev_b64 v[84:85], 7, v[110:111]
	v_lshl_add_u64 v[84:85], s[44:45], 0, v[84:85]
	v_lshl_add_u64 v[84:85], s[52:53], 2, v[84:85]
	s_lshl_b32 s24, s23, 2
	v_lshl_add_u64 v[84:85], v[84:85], 0, s[24:25]
	s_waitcnt lgkmcnt(0)
	v_add_f32_e32 v82, v82, v83
	global_store_dword v[84:85], v82, off
;     __device__ __forceinline__ void operator()(const f32x4 (&acc)[2][2][4][2], const Unit& u, int wr, int wc, int fr, int fq) const {
;     ...
;                 for (int mm = 0; mm < 2; ++mm) { const size_t off = (size_t)(row0 + ai * HALF + (2 * mh + mm) * 16) * ldc + col0;
; #pragma unroll
;                     for (int bj = 0; bj < 2; ++bj) ph[mm][bj] = *(const f16x8v*)(xh + off + bj * HALF); }
; #pragma unroll
;                 for (int mm = 0; mm < 2; ++mm)
; #pragma unroll
;                     for (int bj = 0; bj < 2; ++bj) pre[mm][bj] = __builtin_convertvector(ph[mm][bj], f32x8v);
;             }
; #pragma unroll
;             for (int mm = 0; mm < 2; ++mm) {
;                 const int m = 2 * mh + mm;
;                 const int row = row0 + ai * HALF + m * 16; const size_t off = (size_t)row * ldc + col0;
;                 float q = 0.f;
; #pragma unroll
;                 for (int bj = 0; bj < 2; ++bj) {
;                     const f32x8v o = pre[mm][bj] + __builtin_shufflevector(acc[ai][bj][m][0], acc[ai][bj][m][1], 0, 1, 2, 3, 4, 5, 6, 7);
;                     if (!(pf & 2)) *(f16x8v*)(xh + off + bj * HALF) = __builtin_convertvector(o, f16x8v);
;                     q += ((o[0] * o[0] + o[1] * o[1]) + (o[2] * o[2] + o[3] * o[3])) + ((o[4] * o[4] + o[5] * o[5]) + (o[6] * o[6] + o[7] * o[7]));
;                 }
;                 if (!(pf & 4)) { q += __shfl_xor(q, 16); q += __shfl_xor(q, 32);
;                 if (fq == 0) ssn[(size_t)row * 32 + u.pn * 4 + wc] = q; }
.LBB0_354:
	s_or_b64 exec, exec, s[54:55]
	s_waitcnt vmcnt(3)
	v_cvt_f32_f16_sdwa v89, v102 dst_sel:DWORD dst_unused:UNUSED_PAD src0_sel:WORD_1
	v_cvt_f32_f16_e32 v88, v102
	v_cvt_f32_f16_sdwa v85, v104 dst_sel:DWORD dst_unused:UNUSED_PAD src0_sel:WORD_1
	v_cvt_f32_f16_sdwa v87, v103 dst_sel:DWORD dst_unused:UNUSED_PAD src0_sel:WORD_1
	v_cvt_f32_f16_e32 v84, v104
	v_cvt_f32_f16_e32 v86, v103
	s_waitcnt lgkmcnt(0)
	v_cvt_f32_f16_sdwa v83, v105 dst_sel:DWORD dst_unused:UNUSED_PAD src0_sel:WORD_1
	v_cvt_f32_f16_e32 v82, v105
	v_pk_add_f32 v[78:79], v[78:79], v[88:89]
	v_pk_add_f32 v[80:81], v[80:81], v[86:87]
	v_pk_add_f32 v[84:85], v[74:75], v[84:85]
	v_cvt_pk_f16_f32 v74, v78, v79
	v_mul_f32_e32 v79, v79, v79
	v_fmac_f32_e32 v79, v78, v78
	v_mul_f32_e32 v78, v81, v81
	s_waitcnt vmcnt(2)
	v_cvt_f32_f16_sdwa v95, v99 dst_sel:DWORD dst_unused:UNUSED_PAD src0_sel:WORD_1
	v_cvt_f32_f16_sdwa v97, v98 dst_sel:DWORD dst_unused:UNUSED_PAD src0_sel:WORD_1
	v_cvt_f32_f16_e32 v94, v99
	v_cvt_f32_f16_e32 v96, v98
	v_pk_add_f32 v[82:83], v[76:77], v[82:83]
	v_fmac_f32_e32 v78, v80, v80
	v_cvt_f32_f16_sdwa v91, v101 dst_sel:DWORD dst_unused:UNUSED_PAD src0_sel:WORD_1
	v_cvt_f32_f16_sdwa v93, v100 dst_sel:DWORD dst_unused:UNUSED_PAD src0_sel:WORD_1
	v_cvt_f32_f16_e32 v90, v101
	v_cvt_f32_f16_e32 v92, v100
	v_cvt_pk_f16_f32 v75, v80, v81
	v_add_f32_e32 v78, v79, v78
	v_mul_f32_e32 v79, v85, v85
	v_mul_f32_e32 v80, v83, v83
	v_fmac_f32_e32 v79, v84, v84
	v_fmac_f32_e32 v80, v82, v82
	v_add_f32_e32 v79, v79, v80
	v_cvt_pk_f16_f32 v77, v82, v83
	v_add_f32_e32 v82, v78, v79
	v_pk_add_f32 v[78:79], v[70:71], v[96:97]
	v_pk_add_f32 v[72:73], v[72:73], v[94:95]
	v_pk_add_f32 v[80:81], v[66:67], v[92:93]
	v_pk_add_f32 v[66:67], v[68:69], v[90:91]
	v_mul_f32_e32 v68, v79, v79
	v_mul_f32_e32 v69, v73, v73
	v_fmac_f32_e32 v68, v78, v78
	v_fmac_f32_e32 v69, v72, v72
	v_add_f32_e32 v68, v68, v69
	v_mul_f32_e32 v69, v81, v81
	v_mul_f32_e32 v70, v67, v67
	v_fmac_f32_e32 v69, v80, v80
	v_fmac_f32_e32 v70, v66, v66
	v_add_f32_e32 v69, v69, v70
	v_add_f32_e32 v68, v68, v69
	v_add_f32_e32 v70, v82, v68
	v_cvt_pk_f16_f32 v76, v84, v85
	v_mov_b32_e32 v84, v70
	s_nop 1
	v_permlane16_swap_b32_e32 v84, v70
	v_cvt_pk_f16_f32 v71, v66, v67
	v_lshl_add_u64 v[68:69], s[0:1], 0, v[108:109]
	v_lshl_add_u64 v[82:83], v[148:149], 1, v[68:69]
	v_cvt_pk_f16_f32 v69, v72, v73
	s_waitcnt lgkmcnt(0)
	v_add_f32_e32 v66, v70, v84
	v_mov_b32_e32 v67, v66
	s_nop 1
	v_permlane32_swap_b32_e32 v67, v66
	v_cvt_pk_f16_f32 v70, v80, v81
	v_cvt_pk_f16_f32 v68, v78, v79
	global_store_dwordx4 v[82:83], v[74:77], off
	global_store_dwordx4 v[82:83], v[68:71], off offset:256
	s_and_saveexec_b64 s[54:55], s[36:37]
	s_cbranch_execz .LBB0_356
	v_lshlrev_b64 v[68:69], 7, v[106:107]
	v_lshl_add_u64 v[68:69], s[44:45], 0, v[68:69]
	v_lshl_add_u64 v[68:69], s[52:53], 2, v[68:69]
	s_lshl_b32 s24, s23, 2
	v_lshl_add_u64 v[68:69], v[68:69], 0, s[24:25]
	s_waitcnt lgkmcnt(0)
	v_add_f32_e32 v66, v66, v67
	global_store_dword v[68:69], v66, off
.LBB0_356:
	s_or_b64 exec, exec, s[54:55]
	v_add_u32_e32 v78, 0x80, v150
	v_ashrrev_i32_e32 v79, 31, v78
	v_lshlrev_b64 v[88:89], 12, v[78:79]
	s_waitcnt lgkmcnt(0)
	v_lshl_add_u64 v[66:67], v[152:153], 0, v[88:89]
	global_load_dwordx4 v[80:83], v[66:67], off
	global_load_dwordx4 v[84:87], v[66:67], off offset:256
	v_add_u32_e32 v74, 0x90, v150
	v_ashrrev_i32_e32 v75, 31, v74
	v_lshlrev_b64 v[76:77], 12, v[74:75]
	v_lshl_add_u64 v[66:67], v[152:153], 0, v[76:77]
	global_load_dwordx4 v[70:73], v[66:67], off
	s_nop 0
	global_load_dwordx4 v[66:69], v[66:67], off offset:256
	s_waitcnt vmcnt(3)
	v_cvt_f32_f16_e32 v90, v83
	v_cvt_f32_f16_sdwa v91, v83 dst_sel:DWORD dst_unused:UNUSED_PAD src0_sel:WORD_1
	v_cvt_f32_f16_e32 v92, v82
	v_cvt_f32_f16_sdwa v93, v82 dst_sel:DWORD dst_unused:UNUSED_PAD src0_sel:WORD_1
	v_cvt_f32_f16_e32 v82, v81
	v_cvt_f32_f16_sdwa v83, v81 dst_sel:DWORD dst_unused:UNUSED_PAD src0_sel:WORD_1
	v_cvt_f32_f16_e32 v94, v80
	v_cvt_f32_f16_sdwa v95, v80 dst_sel:DWORD dst_unused:UNUSED_PAD src0_sel:WORD_1
	s_waitcnt vmcnt(2)
	v_cvt_f32_f16_e32 v80, v87
	v_cvt_f32_f16_sdwa v81, v87 dst_sel:DWORD dst_unused:UNUSED_PAD src0_sel:WORD_1
	v_cvt_f32_f16_e32 v96, v86
	v_cvt_f32_f16_sdwa v97, v86 dst_sel:DWORD dst_unused:UNUSED_PAD src0_sel:WORD_1
	v_cvt_f32_f16_e32 v86, v85
	v_cvt_f32_f16_sdwa v87, v85 dst_sel:DWORD dst_unused:UNUSED_PAD src0_sel:WORD_1
	v_cvt_f32_f16_e32 v98, v84
	v_cvt_f32_f16_sdwa v99, v84 dst_sel:DWORD dst_unused:UNUSED_PAD src0_sel:WORD_1
	v_pk_add_f32 v[62:63], v[62:63], v[94:95]
	v_pk_add_f32 v[64:65], v[64:65], v[82:83]
	v_pk_add_f32 v[58:59], v[58:59], v[92:93]
	v_pk_add_f32 v[60:61], v[60:61], v[90:91]
	v_pk_add_f32 v[82:83], v[54:55], v[98:99]
	v_pk_add_f32 v[56:57], v[56:57], v[86:87]
	v_pk_add_f32 v[84:85], v[50:51], v[96:97]
	v_pk_add_f32 v[54:55], v[52:53], v[80:81]
	v_cvt_pk_f16_f32 v53, v60, v61
	v_cvt_pk_f16_f32 v52, v58, v59
	v_cvt_pk_f16_f32 v51, v64, v65
	v_cvt_pk_f16_f32 v50, v62, v63
	v_mul_f32_e32 v63, v63, v63
	v_mul_f32_e32 v65, v65, v65
	v_mul_f32_e32 v59, v59, v59
	v_mul_f32_e32 v61, v61, v61
	v_mul_f32_e32 v80, v83, v83
	v_mul_f32_e32 v81, v57, v57
	v_mul_f32_e32 v86, v85, v85
	v_mul_f32_e32 v87, v55, v55
	v_fmac_f32_e32 v63, v62, v62
	v_fmac_f32_e32 v65, v64, v64
	v_fmac_f32_e32 v59, v58, v58
	v_fmac_f32_e32 v61, v60, v60
	v_fmac_f32_e32 v80, v82, v82
	v_fmac_f32_e32 v81, v56, v56
	v_fmac_f32_e32 v86, v84, v84
	v_fmac_f32_e32 v87, v54, v54
	v_add_f32_e32 v58, v63, v65
	v_add_f32_e32 v59, v59, v61
	v_add_f32_e32 v60, v80, v81
	v_add_f32_e32 v61, v86, v87
	v_add_f32_e32 v58, v58, v59
	v_add_f32_e32 v59, v60, v61
	v_add_f32_e32 v60, v58, v59
	v_mov_b32_e32 v61, v60
	s_nop 1
	v_permlane16_swap_b32_e32 v61, v60
	v_lshl_add_u64 v[58:59], s[0:1], 0, v[88:89]
	v_lshl_add_u64 v[58:59], v[148:149], 1, v[58:59]
	global_store_dwordx4 v[58:59], v[50:53], off
	v_cvt_pk_f16_f32 v55, v54, v55
	v_cvt_pk_f16_f32 v54, v84, v85
	s_waitcnt lgkmcnt(0)
	v_add_f32_e32 v50, v60, v61
	v_mov_b32_e32 v51, v50
	s_nop 1
	v_permlane32_swap_b32_e32 v51, v50
	v_cvt_pk_f16_f32 v53, v56, v57
	v_cvt_pk_f16_f32 v52, v82, v83
	global_store_dwordx4 v[58:59], v[52:55], off offset:256
	s_and_saveexec_b64 s[54:55], s[36:37]
	s_cbranch_execz .LBB0_358
	v_lshlrev_b64 v[52:53], 7, v[78:79]
	v_lshl_add_u64 v[52:53], s[44:45], 0, v[52:53]
	v_lshl_add_u64 v[52:53], s[52:53], 2, v[52:53]
	s_lshl_b32 s24, s23, 2
	v_lshl_add_u64 v[52:53], v[52:53], 0, s[24:25]
	s_waitcnt lgkmcnt(0)
	v_add_f32_e32 v50, v50, v51
	global_store_dword v[52:53], v50, off
;     __device__ __forceinline__ void operator()(const f32x4 (&acc)[2][2][4][2], const Unit& u, int wr, int wc, int fr, int fq) const {
;     ...
;                 for (int mm = 0; mm < 2; ++mm) { const size_t off = (size_t)(row0 + ai * HALF + (2 * mh + mm) * 16) * ldc + col0;
; #pragma unroll
;                     for (int bj = 0; bj < 2; ++bj) ph[mm][bj] = *(const f16x8v*)(xh + off + bj * HALF); }
; #pragma unroll
;                 for (int mm = 0; mm < 2; ++mm)
; #pragma unroll
;                     for (int bj = 0; bj < 2; ++bj) pre[mm][bj] = __builtin_convertvector(ph[mm][bj], f32x8v);
;             }
; #pragma unroll
;             for (int mm = 0; mm < 2; ++mm) {
;                 const int m = 2 * mh + mm;
;                 const int row = row0 + ai * HALF + m * 16; const size_t off = (size_t)row * ldc + col0;
;                 float q = 0.f;
; #pragma unroll
;                 for (int bj = 0; bj < 2; ++bj) {
;                     const f32x8v o = pre[mm][bj] + __builtin_shufflevector(acc[ai][bj][m][0], acc[ai][bj][m][1], 0, 1, 2, 3, 4, 5, 6, 7);
;                     if (!(pf & 2)) *(f16x8v*)(xh + off + bj * HALF) = __builtin_convertvector(o, f16x8v);
;                     q += ((o[0] * o[0] + o[1] * o[1]) + (o[2] * o[2] + o[3] * o[3])) + ((o[4] * o[4] + o[5] * o[5]) + (o[6] * o[6] + o[7] * o[7]));
;                 }
;                 if (!(pf & 4)) { q += __shfl_xor(q, 16); q += __shfl_xor(q, 32);
;                 if (fq == 0) ssn[(size_t)row * 32 + u.pn * 4 + wc] = q; }
.LBB0_358:
	s_or_b64 exec, exec, s[54:55]
	s_waitcnt vmcnt(3)
	v_cvt_f32_f16_sdwa v57, v70 dst_sel:DWORD dst_unused:UNUSED_PAD src0_sel:WORD_1
	v_cvt_f32_f16_e32 v56, v70
	v_cvt_f32_f16_sdwa v53, v72 dst_sel:DWORD dst_unused:UNUSED_PAD src0_sel:WORD_1
	v_cvt_f32_f16_sdwa v55, v71 dst_sel:DWORD dst_unused:UNUSED_PAD src0_sel:WORD_1
	v_cvt_f32_f16_e32 v52, v72
	v_cvt_f32_f16_e32 v54, v71
	s_waitcnt lgkmcnt(0)
	v_cvt_f32_f16_sdwa v51, v73 dst_sel:DWORD dst_unused:UNUSED_PAD src0_sel:WORD_1
	v_cvt_f32_f16_e32 v50, v73
	v_pk_add_f32 v[46:47], v[46:47], v[56:57]
	v_pk_add_f32 v[48:49], v[48:49], v[54:55]
	v_pk_add_f32 v[52:53], v[42:43], v[52:53]
	v_cvt_pk_f16_f32 v42, v46, v47
	v_mul_f32_e32 v47, v47, v47
	v_fmac_f32_e32 v47, v46, v46
	v_mul_f32_e32 v46, v49, v49
	s_waitcnt vmcnt(2)
	v_cvt_f32_f16_sdwa v63, v67 dst_sel:DWORD dst_unused:UNUSED_PAD src0_sel:WORD_1
	v_cvt_f32_f16_sdwa v65, v66 dst_sel:DWORD dst_unused:UNUSED_PAD src0_sel:WORD_1
	v_cvt_f32_f16_e32 v62, v67
	v_cvt_f32_f16_e32 v64, v66
	v_pk_add_f32 v[50:51], v[44:45], v[50:51]
	v_fmac_f32_e32 v46, v48, v48
	v_cvt_f32_f16_sdwa v59, v69 dst_sel:DWORD dst_unused:UNUSED_PAD src0_sel:WORD_1
	v_cvt_f32_f16_sdwa v61, v68 dst_sel:DWORD dst_unused:UNUSED_PAD src0_sel:WORD_1
	v_cvt_f32_f16_e32 v58, v69
	v_cvt_f32_f16_e32 v60, v68
	v_cvt_pk_f16_f32 v43, v48, v49
	v_add_f32_e32 v46, v47, v46
	v_mul_f32_e32 v47, v53, v53
	v_mul_f32_e32 v48, v51, v51
	v_fmac_f32_e32 v47, v52, v52
	v_fmac_f32_e32 v48, v50, v50
	v_add_f32_e32 v47, v47, v48
	v_cvt_pk_f16_f32 v45, v50, v51
	v_add_f32_e32 v50, v46, v47
	v_pk_add_f32 v[46:47], v[38:39], v[64:65]
	v_pk_add_f32 v[40:41], v[40:41], v[62:63]
	v_pk_add_f32 v[48:49], v[34:35], v[60:61]
	v_pk_add_f32 v[34:35], v[36:37], v[58:59]
	v_mul_f32_e32 v36, v47, v47
	v_mul_f32_e32 v37, v41, v41
	v_fmac_f32_e32 v36, v46, v46
	v_fmac_f32_e32 v37, v40, v40
	v_add_f32_e32 v36, v36, v37
	v_mul_f32_e32 v37, v49, v49
	v_mul_f32_e32 v38, v35, v35
	v_fmac_f32_e32 v37, v48, v48
	v_fmac_f32_e32 v38, v34, v34
	v_add_f32_e32 v37, v37, v38
	v_add_f32_e32 v36, v36, v37
	v_add_f32_e32 v38, v50, v36
	v_cvt_pk_f16_f32 v44, v52, v53
	v_mov_b32_e32 v52, v38
	s_nop 1
	v_permlane16_swap_b32_e32 v52, v38
	v_cvt_pk_f16_f32 v39, v34, v35
	v_lshl_add_u64 v[36:37], s[0:1], 0, v[76:77]
	v_lshl_add_u64 v[50:51], v[148:149], 1, v[36:37]
	v_cvt_pk_f16_f32 v37, v40, v41
	s_waitcnt lgkmcnt(0)
	v_add_f32_e32 v34, v38, v52
	v_mov_b32_e32 v35, v34
	s_nop 1
	v_permlane32_swap_b32_e32 v35, v34
	v_cvt_pk_f16_f32 v38, v48, v49
	v_cvt_pk_f16_f32 v36, v46, v47
	global_store_dwordx4 v[50:51], v[42:45], off
	global_store_dwordx4 v[50:51], v[36:39], off offset:256
	s_and_saveexec_b64 s[54:55], s[36:37]
	s_cbranch_execz .LBB0_360
	v_lshlrev_b64 v[36:37], 7, v[74:75]
	v_lshl_add_u64 v[36:37], s[44:45], 0, v[36:37]
	v_lshl_add_u64 v[36:37], s[52:53], 2, v[36:37]
	s_lshl_b32 s24, s23, 2
	v_lshl_add_u64 v[36:37], v[36:37], 0, s[24:25]
	s_waitcnt lgkmcnt(0)
	v_add_f32_e32 v34, v34, v35
	global_store_dword v[36:37], v34, off
;     __device__ __forceinline__ void operator()(const f32x4 (&acc)[2][2][4][2], const Unit& u, int wr, int wc, int fr, int fq) const {
;     ...
;                 for (int mm = 0; mm < 2; ++mm) { const size_t off = (size_t)(row0 + ai * HALF + (2 * mh + mm) * 16) * ldc + col0;
; #pragma unroll
;                     for (int bj = 0; bj < 2; ++bj) ph[mm][bj] = *(const f16x8v*)(xh + off + bj * HALF); }
; #pragma unroll
;                 for (int mm = 0; mm < 2; ++mm)
; #pragma unroll
;                     for (int bj = 0; bj < 2; ++bj) pre[mm][bj] = __builtin_convertvector(ph[mm][bj], f32x8v);
;             }
; #pragma unroll
;             for (int mm = 0; mm < 2; ++mm) {
;                 const int m = 2 * mh + mm;
;                 const int row = row0 + ai * HALF + m * 16; const size_t off = (size_t)row * ldc + col0;
;                 float q = 0.f;
; #pragma unroll
;                 for (int bj = 0; bj < 2; ++bj) {
;                     const f32x8v o = pre[mm][bj] + __builtin_shufflevector(acc[ai][bj][m][0], acc[ai][bj][m][1], 0, 1, 2, 3, 4, 5, 6, 7);
;                     if (!(pf & 2)) *(f16x8v*)(xh + off + bj * HALF) = __builtin_convertvector(o, f16x8v);
;                     q += ((o[0] * o[0] + o[1] * o[1]) + (o[2] * o[2] + o[3] * o[3])) + ((o[4] * o[4] + o[5] * o[5]) + (o[6] * o[6] + o[7] * o[7]));
;                 }
;                 if (!(pf & 4)) { q += __shfl_xor(q, 16); q += __shfl_xor(q, 32);
;                 if (fq == 0) ssn[(size_t)row * 32 + u.pn * 4 + wc] = q; }
.LBB0_360:
	s_or_b64 exec, exec, s[54:55]
	v_add_u32_e32 v46, 0xa0, v150
	v_ashrrev_i32_e32 v47, 31, v46
	v_lshlrev_b64 v[56:57], 12, v[46:47]
	s_waitcnt lgkmcnt(0)
	v_lshl_add_u64 v[34:35], v[152:153], 0, v[56:57]
	global_load_dwordx4 v[48:51], v[34:35], off
	global_load_dwordx4 v[52:55], v[34:35], off offset:256
	v_add_u32_e32 v42, 0xb0, v150
	v_ashrrev_i32_e32 v43, 31, v42
	v_lshlrev_b64 v[44:45], 12, v[42:43]
	v_lshl_add_u64 v[34:35], v[152:153], 0, v[44:45]
	global_load_dwordx4 v[38:41], v[34:35], off
	s_nop 0
	global_load_dwordx4 v[34:37], v[34:35], off offset:256
	s_waitcnt vmcnt(3)
	v_cvt_f32_f16_e32 v58, v51
	v_cvt_f32_f16_sdwa v59, v51 dst_sel:DWORD dst_unused:UNUSED_PAD src0_sel:WORD_1
	v_cvt_f32_f16_e32 v60, v50
	v_cvt_f32_f16_sdwa v61, v50 dst_sel:DWORD dst_unused:UNUSED_PAD src0_sel:WORD_1
	v_cvt_f32_f16_e32 v50, v49
	v_cvt_f32_f16_sdwa v51, v49 dst_sel:DWORD dst_unused:UNUSED_PAD src0_sel:WORD_1
	v_cvt_f32_f16_e32 v62, v48
	v_cvt_f32_f16_sdwa v63, v48 dst_sel:DWORD dst_unused:UNUSED_PAD src0_sel:WORD_1
	s_waitcnt vmcnt(2)
	v_cvt_f32_f16_e32 v48, v55
	v_cvt_f32_f16_sdwa v49, v55 dst_sel:DWORD dst_unused:UNUSED_PAD src0_sel:WORD_1
	v_cvt_f32_f16_e32 v64, v54
	v_cvt_f32_f16_sdwa v65, v54 dst_sel:DWORD dst_unused:UNUSED_PAD src0_sel:WORD_1
	v_cvt_f32_f16_e32 v54, v53
	v_cvt_f32_f16_sdwa v55, v53 dst_sel:DWORD dst_unused:UNUSED_PAD src0_sel:WORD_1
	v_cvt_f32_f16_e32 v66, v52
	v_cvt_f32_f16_sdwa v67, v52 dst_sel:DWORD dst_unused:UNUSED_PAD src0_sel:WORD_1
	v_pk_add_f32 v[30:31], v[30:31], v[62:63]
	v_pk_add_f32 v[32:33], v[32:33], v[50:51]
	v_pk_add_f32 v[26:27], v[26:27], v[60:61]
	v_pk_add_f32 v[28:29], v[28:29], v[58:59]
	v_pk_add_f32 v[50:51], v[22:23], v[66:67]
	v_pk_add_f32 v[24:25], v[24:25], v[54:55]
	v_pk_add_f32 v[52:53], v[18:19], v[64:65]
	v_pk_add_f32 v[22:23], v[20:21], v[48:49]
	v_cvt_pk_f16_f32 v21, v28, v29
	v_cvt_pk_f16_f32 v20, v26, v27
	v_cvt_pk_f16_f32 v19, v32, v33
	v_cvt_pk_f16_f32 v18, v30, v31
	v_mul_f32_e32 v31, v31, v31
	v_mul_f32_e32 v33, v33, v33
	v_mul_f32_e32 v27, v27, v27
	v_mul_f32_e32 v29, v29, v29
	v_mul_f32_e32 v48, v51, v51
	v_mul_f32_e32 v49, v25, v25
	v_mul_f32_e32 v54, v53, v53
	v_mul_f32_e32 v55, v23, v23
	v_fmac_f32_e32 v31, v30, v30
	v_fmac_f32_e32 v33, v32, v32
	v_fmac_f32_e32 v27, v26, v26
	v_fmac_f32_e32 v29, v28, v28
	v_fmac_f32_e32 v48, v50, v50
	v_fmac_f32_e32 v49, v24, v24
	v_fmac_f32_e32 v54, v52, v52
	v_fmac_f32_e32 v55, v22, v22
	v_add_f32_e32 v26, v31, v33
	v_add_f32_e32 v27, v27, v29
	v_add_f32_e32 v28, v48, v49
	v_add_f32_e32 v29, v54, v55
	v_add_f32_e32 v26, v26, v27
	v_add_f32_e32 v27, v28, v29
	v_add_f32_e32 v28, v26, v27
	v_mov_b32_e32 v29, v28
	s_nop 1
	v_permlane16_swap_b32_e32 v29, v28
	v_lshl_add_u64 v[26:27], s[0:1], 0, v[56:57]
	v_lshl_add_u64 v[26:27], v[148:149], 1, v[26:27]
	global_store_dwordx4 v[26:27], v[18:21], off
	v_cvt_pk_f16_f32 v23, v22, v23
	v_cvt_pk_f16_f32 v22, v52, v53
	s_waitcnt lgkmcnt(0)
	v_add_f32_e32 v18, v28, v29
	v_mov_b32_e32 v19, v18
	s_nop 1
	v_permlane32_swap_b32_e32 v19, v18
	v_cvt_pk_f16_f32 v21, v24, v25
	v_cvt_pk_f16_f32 v20, v50, v51
	global_store_dwordx4 v[26:27], v[20:23], off offset:256
	s_and_saveexec_b64 s[54:55], s[36:37]
	s_cbranch_execz .LBB0_362
	v_lshlrev_b64 v[20:21], 7, v[46:47]
	v_lshl_add_u64 v[20:21], s[44:45], 0, v[20:21]
	v_lshl_add_u64 v[20:21], s[52:53], 2, v[20:21]
	s_lshl_b32 s24, s23, 2
	v_lshl_add_u64 v[20:21], v[20:21], 0, s[24:25]
	s_waitcnt lgkmcnt(0)
	v_add_f32_e32 v18, v18, v19
	global_store_dword v[20:21], v18, off
.LBB0_362:
	s_or_b64 exec, exec, s[54:55]
	s_waitcnt vmcnt(3)
	v_cvt_f32_f16_sdwa v25, v38 dst_sel:DWORD dst_unused:UNUSED_PAD src0_sel:WORD_1
	v_cvt_f32_f16_e32 v24, v38
	v_cvt_f32_f16_sdwa v21, v40 dst_sel:DWORD dst_unused:UNUSED_PAD src0_sel:WORD_1
	v_cvt_f32_f16_sdwa v23, v39 dst_sel:DWORD dst_unused:UNUSED_PAD src0_sel:WORD_1
	v_cvt_f32_f16_e32 v20, v40
	v_cvt_f32_f16_e32 v22, v39
	s_waitcnt lgkmcnt(0)
	v_cvt_f32_f16_sdwa v19, v41 dst_sel:DWORD dst_unused:UNUSED_PAD src0_sel:WORD_1
	v_cvt_f32_f16_e32 v18, v41
	v_pk_add_f32 v[14:15], v[14:15], v[24:25]
	v_pk_add_f32 v[16:17], v[16:17], v[22:23]
	v_pk_add_f32 v[20:21], v[10:11], v[20:21]
	v_cvt_pk_f16_f32 v10, v14, v15
	v_mul_f32_e32 v15, v15, v15
	v_fmac_f32_e32 v15, v14, v14
	v_mul_f32_e32 v14, v17, v17
	s_waitcnt vmcnt(2)
	v_cvt_f32_f16_sdwa v31, v35 dst_sel:DWORD dst_unused:UNUSED_PAD src0_sel:WORD_1
	v_cvt_f32_f16_sdwa v33, v34 dst_sel:DWORD dst_unused:UNUSED_PAD src0_sel:WORD_1
	v_cvt_f32_f16_e32 v30, v35
	v_cvt_f32_f16_e32 v32, v34
	v_pk_add_f32 v[18:19], v[12:13], v[18:19]
	v_fmac_f32_e32 v14, v16, v16
	v_cvt_f32_f16_sdwa v27, v37 dst_sel:DWORD dst_unused:UNUSED_PAD src0_sel:WORD_1
	v_cvt_f32_f16_sdwa v29, v36 dst_sel:DWORD dst_unused:UNUSED_PAD src0_sel:WORD_1
	v_cvt_f32_f16_e32 v26, v37
	v_cvt_f32_f16_e32 v28, v36
	v_cvt_pk_f16_f32 v11, v16, v17
	v_add_f32_e32 v14, v15, v14
	v_mul_f32_e32 v15, v21, v21
	v_mul_f32_e32 v16, v19, v19
	v_fmac_f32_e32 v15, v20, v20
	v_fmac_f32_e32 v16, v18, v18
	v_add_f32_e32 v15, v15, v16
	v_cvt_pk_f16_f32 v13, v18, v19
	v_add_f32_e32 v18, v14, v15
	v_pk_add_f32 v[14:15], v[6:7], v[32:33]
	v_pk_add_f32 v[8:9], v[8:9], v[30:31]
	v_pk_add_f32 v[16:17], v[2:3], v[28:29]
	v_pk_add_f32 v[2:3], v[4:5], v[26:27]
	v_mul_f32_e32 v4, v15, v15
	v_mul_f32_e32 v5, v9, v9
	v_fmac_f32_e32 v4, v14, v14
	v_fmac_f32_e32 v5, v8, v8
	v_add_f32_e32 v4, v4, v5
	v_mul_f32_e32 v5, v17, v17
	v_mul_f32_e32 v6, v3, v3
	v_fmac_f32_e32 v5, v16, v16
	v_fmac_f32_e32 v6, v2, v2
	v_add_f32_e32 v5, v5, v6
	v_add_f32_e32 v4, v4, v5
	v_add_f32_e32 v6, v18, v4
	v_cvt_pk_f16_f32 v12, v20, v21
	v_mov_b32_e32 v20, v6
	s_nop 1
	v_permlane16_swap_b32_e32 v20, v6
	v_cvt_pk_f16_f32 v7, v2, v3
	v_lshl_add_u64 v[4:5], s[0:1], 0, v[44:45]
	v_lshl_add_u64 v[18:19], v[148:149], 1, v[4:5]
	v_cvt_pk_f16_f32 v5, v8, v9
	s_waitcnt lgkmcnt(0)
	v_add_f32_e32 v2, v6, v20
	v_mov_b32_e32 v3, v2
	s_nop 1
	v_permlane32_swap_b32_e32 v3, v2
	v_cvt_pk_f16_f32 v6, v16, v17
	v_cvt_pk_f16_f32 v4, v14, v15
	global_store_dwordx4 v[18:19], v[10:13], off
	global_store_dwordx4 v[18:19], v[4:7], off offset:256
	s_and_saveexec_b64 s[54:55], s[36:37]
	s_cbranch_execz .LBB0_364
	v_lshlrev_b64 v[4:5], 7, v[42:43]
	v_lshl_add_u64 v[4:5], s[44:45], 0, v[4:5]
	v_lshl_add_u64 v[4:5], s[52:53], 2, v[4:5]
	s_lshl_b32 s24, s23, 2
	v_lshl_add_u64 v[4:5], v[4:5], 0, s[24:25]
	s_waitcnt lgkmcnt(0)
	v_add_f32_e32 v2, v2, v3
	global_store_dword v[4:5], v2, off
